# P0 norm: each block takes 72 consecutive token rows, so the adaLN shift/scale vectors stay in registers (reloaded only when the row's batch changes)
# speedup vs baseline: 1.0116x; 1.0022x over previous
; #define OPQ int tid = tid0; asm volatile("" : "+v"(tid));
; DEV void norm_item(const Params& p, int l, int g, int item, int tid) {
;   const int wid = tid >> 6, lane = tid & 63;
;   const int r = item * 8 + wid;
;   const int bl = r / NTOK, j = r % NTOK, b = g * G + bl;
;   const float* src;
;   int mrow;
;   if (j < NCTX) {
;     src = (l == 0 ? p.ctx : p.hctx) + ((long)b * NCTX + j) * D;
;     mrow = 32;
;   } else {
;     src = (l == 0 ? p.x : p.out) + ((long)b * SEQ + (j - NCTX)) * D;
;     mrow = b;
;   }
;   const float* md = p.mod + ((long)l * 33 + mrow) * 3072;
;   const float* ng = p.norm_g + l * D;
; __global__ void __launch_bounds__(512) mega(Params p, int coop) {
;     ...
;         for (int it = bid; it < TG / 8; it += nb) { OPQ norm_item(p, l, g, it, tid); }
.LBB0_104:
	s_cmp_eq_u32 s14, 0
	s_cselect_b64 s[6:7], -1, 0
	v_writelane_b32 v255, s6, 38
	s_lshl_b32 s24, s14, 10
	s_nop 0
	v_writelane_b32 v255, s7, 39
	v_readlane_b32 s6, v253, 23
	v_readlane_b32 s7, v253, 24
	s_andn2_b64 vcc, exec, s[6:7]
	s_cbranch_vccnz .LBB0_111
	v_readlane_b32 s6, v255, 38
	v_readlane_b32 s7, v255, 39
	s_and_b64 s[6:7], s[6:7], exec
	s_cselect_b32 s6, 0, 0x98
	s_cselect_b32 s8, 16, 0xe0
	s_lshl_b64 s[12:13], s[24:25], 2
	v_readlane_b32 s16, v255, 15
	v_readlane_b32 s17, v255, 16
	s_add_u32 s16, s16, s12
	s_mov_b32 s7, s25
	s_mov_b32 s9, s25
	s_mul_i32 s10, s14, 33
	s_mov_b32 s11, s25
	s_addc_u32 s17, s17, s13
	v_readlane_b32 s15, v254, 36
	s_mov_b32 s18, s75
	v_readlane_b32 s12, v253, 0
	v_readlane_b32 s13, v253, 1
	v_lshrrev_b32_e32 v0, 6, v197
	s_load_dwordx2 s[56:57], s[12:13], s6
	s_load_dwordx2 s[58:59], s[12:13], s8
	v_and_b32_e32 v1, 63, v197
	v_readfirstlane_b32 s60, v0
	v_lshlrev_b32_e32 v156, 4, v1
	v_lshlrev_b32_e32 v50, 3, v1
	v_lshlrev_b32_e32 v51, 2, v197
	v_xor_b32_e32 v64, 0x80, v51
	v_and_b32_e32 v64, 0xfc, v64
	v_xor_b32_e32 v65, 0x40, v51
	v_and_b32_e32 v65, 0xfc, v65
	v_xor_b32_e32 v66, 0x20, v51
	v_and_b32_e32 v66, 0xfc, v66
	v_xor_b32_e32 v67, 0x10, v51
	v_and_b32_e32 v67, 0xfc, v67
	v_xor_b32_e32 v68, 0x8, v51
	v_and_b32_e32 v68, 0xfc, v68
	v_xor_b32_e32 v69, 0x4, v51
	v_and_b32_e32 v69, 0xfc, v69
	s_waitcnt lgkmcnt(0)
	s_mov_b32 s46, 0x800000
	s_mul_i32 s18, s75, 9
	s_lshl_b32 s15, s18, 3
	s_add_i32 s47, s18, 9
	s_mov_b32 s98, -1
	s_mov_b32 s99, -1
	s_mov_b64 s[48:49], s[56:57]
	global_load_dwordx4 v[96:99], v156, s[16:17]
	global_load_dwordx4 v[100:103], v156, s[16:17] offset:1024
	global_load_dwordx4 v[104:107], v156, s[16:17] offset:2048
	global_load_dwordx4 v[108:111], v156, s[16:17] offset:3072
	s_mov_b32 s44, 0
	s_cmp_ge_u32 s18, s47
	s_cbranch_scc1 .Lp0_skipA_0
	s_mov_b32 s44, 1
	s_add_i32 s19, s15, s60
	s_mul_hi_u32 s32, s19, 0x38e38e39
	s_lshr_b32 s32, s32, 9
	s_mul_i32 s11, s32, 0x900
	s_sub_i32 s61, s19, s11
	s_lshl_b32 s12, s19, 11
	s_add_u32 s12, s86, s12
	s_addc_u32 s13, s87, 0
	v_readlane_b32 s19, v255, 29
	s_nop 0
	s_add_i32 s32, s32, s19
	s_add_i32 s19, s61, 0xffffff00
	s_cmp_lt_u32 s61, 0x100
	s_cselect_b32 s62, s58, s48
	s_cselect_b32 s63, s59, s49
	s_cselect_b32 s11, 20, 23
	s_cselect_b32 s79, 32, s32
	s_cselect_b32 s19, s61, s19
	s_lshl_b32 s32, s32, s11
	s_lshl_b32 s19, s19, 12
	s_add_u32 s32, s32, s19
	s_add_u32 s62, s62, s32
	s_addc_u32 s63, s63, 0
	s_add_i32 s79, s79, s10
	s_mul_i32 s79, s79, 0x3000
	v_readlane_b32 s19, v253, 21
	v_readlane_b32 s32, v253, 22
	s_nop 0
	s_add_u32 s6, s19, s79
	s_addc_u32 s7, s32, 0
	s_add_u32 s8, s6, 0x1000
	s_addc_u32 s9, s7, 0
	global_load_dwordx4 v[4:7], v156, s[62:63]
	global_load_dwordx4 v[8:11], v156, s[62:63] offset:1024
	global_load_dwordx4 v[12:15], v156, s[62:63] offset:2048
	global_load_dwordx4 v[16:19], v156, s[62:63] offset:3072
	s_cmp_eq_u32 s6, s98
	s_cbranch_scc1 .Lp0_skipA_0_same
	s_mov_b32 s98, s6
	global_load_dwordx4 v[200:203], v156, s[8:9]
	global_load_dwordx4 v[174:177], v156, s[6:7]
	global_load_dwordx4 v[204:207], v156, s[8:9] offset:1024
	global_load_dwordx4 v[178:181], v156, s[6:7] offset:1024
	global_load_dwordx4 v[208:211], v156, s[8:9] offset:2048
	global_load_dwordx4 v[182:185], v156, s[6:7] offset:2048
	global_load_dwordx4 v[212:215], v156, s[8:9] offset:3072
	global_load_dwordx4 v[186:189], v156, s[6:7] offset:3072
.Lp0_skipA_0_same:
	s_add_i32 s18, s18, 1
	s_add_i32 s15, s15, 8
.Lp0_skipA_0:
	s_mov_b32 s45, 0
	s_cmp_ge_u32 s18, s47
	s_cbranch_scc1 .Lp0_skipB_1
	s_mov_b32 s45, 1
	s_add_i32 s19, s15, s60
	s_mul_hi_u32 s32, s19, 0x38e38e39
	s_lshr_b32 s32, s32, 9
	s_mul_i32 s11, s32, 0x900
	s_sub_i32 s61, s19, s11
	s_lshl_b32 s54, s19, 11
	s_add_u32 s54, s86, s54
	s_addc_u32 s55, s87, 0
	v_readlane_b32 s19, v255, 29
	s_nop 0
	s_add_i32 s32, s32, s19
	s_add_i32 s19, s61, 0xffffff00
	s_cmp_lt_u32 s61, 0x100
	s_cselect_b32 s56, s58, s48
	s_cselect_b32 s57, s59, s49
	s_cselect_b32 s11, 20, 23
	s_cselect_b32 s79, 32, s32
	s_cselect_b32 s19, s61, s19
	s_lshl_b32 s32, s32, s11
	s_lshl_b32 s19, s19, 12
	s_add_u32 s32, s32, s19
	s_add_u32 s56, s56, s32
	s_addc_u32 s57, s57, 0
	s_add_i32 s79, s79, s10
	s_mul_i32 s79, s79, 0x3000
	v_readlane_b32 s19, v253, 21
	v_readlane_b32 s32, v253, 22
	s_nop 0
	s_add_u32 s50, s19, s79
	s_addc_u32 s51, s32, 0
	s_add_u32 s52, s50, 0x1000
	s_addc_u32 s53, s51, 0
	global_load_dwordx4 v[136:139], v156, s[56:57]
	global_load_dwordx4 v[140:143], v156, s[56:57] offset:1024
	global_load_dwordx4 v[144:147], v156, s[56:57] offset:2048
	global_load_dwordx4 v[148:151], v156, s[56:57] offset:3072
	s_cmp_eq_u32 s50, s99
	s_cbranch_scc1 .Lp0_skipB_1_same
	s_mov_b32 s99, s50
	global_load_dwordx4 v[216:219], v156, s[52:53]
	global_load_dwordx4 v[158:161], v156, s[50:51]
	global_load_dwordx4 v[220:223], v156, s[52:53] offset:1024
	global_load_dwordx4 v[162:165], v156, s[50:51] offset:1024
	global_load_dwordx4 v[224:227], v156, s[52:53] offset:2048
	global_load_dwordx4 v[166:169], v156, s[50:51] offset:2048
	global_load_dwordx4 v[228:231], v156, s[52:53] offset:3072
	global_load_dwordx4 v[170:173], v156, s[50:51] offset:3072

; DEV void norm_item(const Params& p, int l, int g, int item, int tid) {
;   const int wid = tid >> 6, lane = tid & 63;
;   const int r = item * 8 + wid;
;   const int bl = r / NTOK, j = r % NTOK, b = g * G + bl;
;   const float* src;
;   int mrow;
;   if (j < NCTX) {
;     src = (l == 0 ? p.ctx : p.hctx) + ((long)b * NCTX + j) * D;
;     mrow = 32;
;   } else {
;     src = (l == 0 ? p.x : p.out) + ((long)b * SEQ + (j - NCTX)) * D;
;     mrow = b;
;   }
;   const float* md = p.mod + ((long)l * 33 + mrow) * 3072;
;   const float* ng = p.norm_g + l * D;
;   float4 v[4];
;   float ss = 0.f;
; #pragma unroll
;   for (int i = 0; i < 4; ++i) {
;     v[i] = *(const float4*)(src + i * 256 + lane * 4);
;     ss += v[i].x * v[i].x + v[i].y * v[i].y + v[i].z * v[i].z + v[i].w * v[i].w;
;   }
;   ss = wsum(ss, lane);
;   const float rstd = rsqrtf(ss * (1.f / D) + 1e-6f);
; #pragma unroll
;   for (int i = 0; i < 4; ++i) {
;     int col = i * 256 + lane * 4;
;     float4 gg = *(const float4*)(ng + col);
;     float4 sh = *(const float4*)(md + col);
;     float4 sc = *(const float4*)(md + 1024 + col);
;     uint2 o;
;     o.x = pack2(v[i].x * rstd * gg.x * (1.f + sc.x) + sh.x, v[i].y * rstd * gg.y * (1.f + sc.y) + sh.y);
;     o.y = pack2(v[i].z * rstd * gg.z * (1.f + sc.z) + sh.z, v[i].w * rstd * gg.w * (1.f + sc.w) + sh.w);
;     *(uint2*)(p.u + (long)r * D + col) = o;
;   }
; }
.Lp0_x0:
.Lp0_loop:
	v_mov_b32_e32 v40, v5
	v_mov_b32_e32 v41, v9
	v_mov_b32_e32 v38, v4
	v_mov_b32_e32 v39, v8
	v_mov_b32_e32 v48, v13
	v_mov_b32_e32 v49, v17
	v_pk_mul_f32 v[40:41], v[40:41], v[40:41]
	v_mov_b32_e32 v2, v6
	v_mov_b32_e32 v3, v10
	v_mov_b32_e32 v46, v12
	v_mov_b32_e32 v47, v16
	v_pk_mul_f32 v[48:49], v[48:49], v[48:49]
	v_pk_fma_f32 v[38:39], v[38:39], v[38:39], v[40:41]
	v_mov_b32_e32 v36, v7
	v_mov_b32_e32 v37, v11
	v_mov_b32_e32 v42, v14
	v_mov_b32_e32 v43, v18
	v_pk_fma_f32 v[40:41], v[46:47], v[46:47], v[48:49]
	v_pk_fma_f32 v[2:3], v[2:3], v[2:3], v[38:39]
	v_mov_b32_e32 v44, v15
	v_mov_b32_e32 v45, v19
	v_pk_fma_f32 v[38:39], v[42:43], v[42:43], v[40:41]
	v_pk_fma_f32 v[2:3], v[36:37], v[36:37], v[2:3]
	v_pk_fma_f32 v[36:37], v[44:45], v[44:45], v[38:39]
	v_add_f32_e32 v2, v2, v3
	v_add_f32_e32 v2, v2, v36
	v_add_f32_e32 v2, v2, v37
	ds_bpermute_b32 v1, v64, v2
	s_waitcnt lgkmcnt(0)
	v_add_f32_e32 v1, v2, v1
	ds_bpermute_b32 v2, v65, v1
	s_waitcnt lgkmcnt(0)
	v_add_f32_e32 v1, v1, v2
	ds_bpermute_b32 v2, v66, v1
	s_waitcnt lgkmcnt(0)
	v_add_f32_e32 v2, v1, v2
	ds_bpermute_b32 v3, v67, v2
	s_waitcnt lgkmcnt(0)
	v_add_f32_e32 v2, v2, v3
	ds_bpermute_b32 v36, v68, v2
	s_waitcnt lgkmcnt(0)
	v_add_f32_e32 v40, v2, v36
	ds_bpermute_b32 v41, v69, v40
	s_waitcnt lgkmcnt(0)
	v_add_f32_e32 v0, v40, v41
	v_fmamk_f32 v0, v0, 0x3a800000, v196
	v_mul_f32_e32 v1, 0x4b800000, v0
	v_cmp_gt_f32_e32 vcc, s46, v0
	s_nop 1
	v_cndmask_b32_e32 v0, v0, v1, vcc
	v_rsq_f32_e32 v40, v0
	s_nop 0
	v_mul_f32_e32 v20, 0x45800000, v40
	v_cndmask_b32_e32 v40, v40, v20, vcc
	v_pk_add_f32 v[22:23], v[202:203], 1.0 op_sel_hi:[1,0]
	v_pk_add_f32 v[20:21], v[200:201], 1.0 op_sel_hi:[1,0]
	v_pk_mul_f32 v[24:25], v[4:5], v[40:41] op_sel_hi:[1,0]
	v_pk_mul_f32 v[26:27], v[6:7], v[40:41] op_sel_hi:[1,0]
	v_pk_mul_f32 v[24:25], v[96:97], v[24:25]
	v_pk_mul_f32 v[26:27], v[98:99], v[26:27]
	v_pk_fma_f32 v[20:21], v[20:21], v[24:25], v[174:175]
	v_pk_fma_f32 v[22:23], v[22:23], v[26:27], v[176:177]
	v_cvt_pk_bf16_f32 v70, v20, v21
	v_cvt_pk_bf16_f32 v71, v22, v23
	global_store_dwordx2 v50, v[70:71], s[12:13]
	v_pk_mul_f32 v[24:25], v[8:9], v[40:41] op_sel_hi:[1,0]
	v_pk_mul_f32 v[26:27], v[10:11], v[40:41] op_sel_hi:[1,0]
	v_pk_mul_f32 v[24:25], v[24:25], v[100:101]
	v_pk_mul_f32 v[26:27], v[26:27], v[102:103]
	v_pk_add_f32 v[20:21], v[204:205], 1.0 op_sel_hi:[1,0]
	v_pk_add_f32 v[22:23], v[206:207], 1.0 op_sel_hi:[1,0]
	v_pk_fma_f32 v[20:21], v[24:25], v[20:21], v[178:179]
	v_pk_fma_f32 v[22:23], v[26:27], v[22:23], v[180:181]
	v_cvt_pk_bf16_f32 v72, v20, v21
	v_cvt_pk_bf16_f32 v73, v22, v23
	global_store_dwordx2 v50, v[72:73], s[12:13] offset:512
	v_pk_mul_f32 v[24:25], v[12:13], v[40:41] op_sel_hi:[1,0]
	v_pk_mul_f32 v[26:27], v[14:15], v[40:41] op_sel_hi:[1,0]
	v_pk_mul_f32 v[24:25], v[24:25], v[104:105]
	v_pk_mul_f32 v[26:27], v[26:27], v[106:107]
	v_pk_add_f32 v[20:21], v[208:209], 1.0 op_sel_hi:[1,0]
	v_pk_add_f32 v[22:23], v[210:211], 1.0 op_sel_hi:[1,0]
	v_pk_fma_f32 v[20:21], v[24:25], v[20:21], v[182:183]
	v_pk_fma_f32 v[22:23], v[26:27], v[22:23], v[184:185]
	v_cvt_pk_bf16_f32 v74, v20, v21
	v_cvt_pk_bf16_f32 v75, v22, v23
	global_store_dwordx2 v50, v[74:75], s[12:13] offset:1024
	v_pk_mul_f32 v[24:25], v[16:17], v[40:41] op_sel_hi:[1,0]
	v_pk_mul_f32 v[26:27], v[18:19], v[40:41] op_sel_hi:[1,0]
	v_pk_mul_f32 v[24:25], v[24:25], v[108:109]
	v_pk_mul_f32 v[26:27], v[26:27], v[110:111]
	v_pk_add_f32 v[20:21], v[212:213], 1.0 op_sel_hi:[1,0]
	v_pk_add_f32 v[22:23], v[214:215], 1.0 op_sel_hi:[1,0]
	v_pk_fma_f32 v[20:21], v[24:25], v[20:21], v[186:187]
	v_pk_fma_f32 v[22:23], v[26:27], v[22:23], v[188:189]
	v_cvt_pk_bf16_f32 v76, v20, v21
	v_cvt_pk_bf16_f32 v77, v22, v23
	global_store_dwordx2 v50, v[76:77], s[12:13] offset:1536
	s_cmp_lg_u32 s45, 0
	s_cbranch_scc0 .Lp0_done
	s_mov_b32 s44, 0
	s_cmp_ge_u32 s18, s47
	s_cbranch_scc1 .Lp0_skipA_2
	s_mov_b32 s44, 1
	s_add_i32 s19, s15, s60
	s_mul_hi_u32 s32, s19, 0x38e38e39
	s_lshr_b32 s32, s32, 9
	s_mul_i32 s11, s32, 0x900
	s_sub_i32 s61, s19, s11
	s_lshl_b32 s12, s19, 11
	s_add_u32 s12, s86, s12
	s_addc_u32 s13, s87, 0
	v_readlane_b32 s19, v255, 29
	s_nop 0
	s_add_i32 s32, s32, s19
	s_add_i32 s19, s61, 0xffffff00
	s_cmp_lt_u32 s61, 0x100
	s_cselect_b32 s62, s58, s48
	s_cselect_b32 s63, s59, s49
	s_cselect_b32 s11, 20, 23
	s_cselect_b32 s79, 32, s32
	s_cselect_b32 s19, s61, s19
	s_lshl_b32 s32, s32, s11
	s_lshl_b32 s19, s19, 12
	s_add_u32 s32, s32, s19
	s_add_u32 s62, s62, s32
	s_addc_u32 s63, s63, 0
	s_add_i32 s79, s79, s10
	s_mul_i32 s79, s79, 0x3000
	v_readlane_b32 s19, v253, 21
	v_readlane_b32 s32, v253, 22
	s_nop 0
	s_add_u32 s6, s19, s79
	s_addc_u32 s7, s32, 0
	s_add_u32 s8, s6, 0x1000
	s_addc_u32 s9, s7, 0
	global_load_dwordx4 v[4:7], v156, s[62:63]
	global_load_dwordx4 v[8:11], v156, s[62:63] offset:1024
	global_load_dwordx4 v[12:15], v156, s[62:63] offset:2048
	global_load_dwordx4 v[16:19], v156, s[62:63] offset:3072
	s_cmp_eq_u32 s6, s98
	s_cbranch_scc1 .Lp0_skipA_2_same
	s_mov_b32 s98, s6
	global_load_dwordx4 v[200:203], v156, s[8:9]
	global_load_dwordx4 v[174:177], v156, s[6:7]
	global_load_dwordx4 v[204:207], v156, s[8:9] offset:1024
	global_load_dwordx4 v[178:181], v156, s[6:7] offset:1024
	global_load_dwordx4 v[208:211], v156, s[8:9] offset:2048
	global_load_dwordx4 v[182:185], v156, s[6:7] offset:2048
	global_load_dwordx4 v[212:215], v156, s[8:9] offset:3072
	global_load_dwordx4 v[186:189], v156, s[6:7] offset:3072

; DEV void norm_item(const Params& p, int l, int g, int item, int tid) {
;     ...
;   float ss = 0.f;
; #pragma unroll
;   for (int i = 0; i < 4; ++i) {
;     v[i] = *(const float4*)(src + i * 256 + lane * 4);
;     ss += v[i].x * v[i].x + v[i].y * v[i].y + v[i].z * v[i].z + v[i].w * v[i].w;
;   }
;   ss = wsum(ss, lane);
.Lp0_skipA_2:
	s_cmp_lg_u32 s44, 0
	s_cbranch_scc0 .Lp0_w1
	s_waitcnt vmcnt(8)
	s_branch .Lp0_x1

; DEV void norm_item(const Params& p, int l, int g, int item, int tid) {
;   const int wid = tid >> 6, lane = tid & 63;
;   const int r = item * 8 + wid;
;   const int bl = r / NTOK, j = r % NTOK, b = g * G + bl;
;   const float* src;
;   int mrow;
;   if (j < NCTX) {
;     src = (l == 0 ? p.ctx : p.hctx) + ((long)b * NCTX + j) * D;
;     mrow = 32;
;   } else {
;     src = (l == 0 ? p.x : p.out) + ((long)b * SEQ + (j - NCTX)) * D;
;     mrow = b;
;   }
;   const float* md = p.mod + ((long)l * 33 + mrow) * 3072;
;   const float* ng = p.norm_g + l * D;
;   float4 v[4];
;   float ss = 0.f;
; #pragma unroll
;   for (int i = 0; i < 4; ++i) {
;     v[i] = *(const float4*)(src + i * 256 + lane * 4);
;     ss += v[i].x * v[i].x + v[i].y * v[i].y + v[i].z * v[i].z + v[i].w * v[i].w;
;   }
;   ss = wsum(ss, lane);
;   const float rstd = rsqrtf(ss * (1.f / D) + 1e-6f);
; #pragma unroll
;   for (int i = 0; i < 4; ++i) {
;     int col = i * 256 + lane * 4;
;     float4 gg = *(const float4*)(ng + col);
;     float4 sh = *(const float4*)(md + col);
;     float4 sc = *(const float4*)(md + 1024 + col);
;     uint2 o;
;     o.x = pack2(v[i].x * rstd * gg.x * (1.f + sc.x) + sh.x, v[i].y * rstd * gg.y * (1.f + sc.y) + sh.y);
;     o.y = pack2(v[i].z * rstd * gg.z * (1.f + sc.z) + sh.z, v[i].w * rstd * gg.w * (1.f + sc.w) + sh.w);
;     *(uint2*)(p.u + (long)r * D + col) = o;
;   }
; }
.Lp0_x1:
	v_mov_b32_e32 v40, v137
	v_mov_b32_e32 v41, v141
	v_mov_b32_e32 v38, v136
	v_mov_b32_e32 v39, v140
	v_mov_b32_e32 v48, v145
	v_mov_b32_e32 v49, v149
	v_pk_mul_f32 v[40:41], v[40:41], v[40:41]
	v_mov_b32_e32 v2, v138
	v_mov_b32_e32 v3, v142
	v_mov_b32_e32 v46, v144
	v_mov_b32_e32 v47, v148
	v_pk_mul_f32 v[48:49], v[48:49], v[48:49]
	v_pk_fma_f32 v[38:39], v[38:39], v[38:39], v[40:41]
	v_mov_b32_e32 v36, v139
	v_mov_b32_e32 v37, v143
	v_mov_b32_e32 v42, v146
	v_mov_b32_e32 v43, v150
	v_pk_fma_f32 v[40:41], v[46:47], v[46:47], v[48:49]
	v_pk_fma_f32 v[2:3], v[2:3], v[2:3], v[38:39]
	v_mov_b32_e32 v44, v147
	v_mov_b32_e32 v45, v151
	v_pk_fma_f32 v[38:39], v[42:43], v[42:43], v[40:41]
	v_pk_fma_f32 v[2:3], v[36:37], v[36:37], v[2:3]
	v_pk_fma_f32 v[36:37], v[44:45], v[44:45], v[38:39]
	v_add_f32_e32 v2, v2, v3
	v_add_f32_e32 v2, v2, v36
	v_add_f32_e32 v2, v2, v37
	ds_bpermute_b32 v1, v64, v2
	s_waitcnt lgkmcnt(0)
	v_add_f32_e32 v1, v2, v1
	ds_bpermute_b32 v2, v65, v1
	s_waitcnt lgkmcnt(0)
	v_add_f32_e32 v1, v1, v2
	ds_bpermute_b32 v2, v66, v1
	s_waitcnt lgkmcnt(0)
	v_add_f32_e32 v2, v1, v2
	ds_bpermute_b32 v3, v67, v2
	s_waitcnt lgkmcnt(0)
	v_add_f32_e32 v2, v2, v3
	ds_bpermute_b32 v36, v68, v2
	s_waitcnt lgkmcnt(0)
	v_add_f32_e32 v40, v2, v36
	ds_bpermute_b32 v41, v69, v40
	s_waitcnt lgkmcnt(0)
	v_add_f32_e32 v0, v40, v41
	v_fmamk_f32 v0, v0, 0x3a800000, v196
	v_mul_f32_e32 v1, 0x4b800000, v0
	v_cmp_gt_f32_e32 vcc, s46, v0
	s_nop 1
	v_cndmask_b32_e32 v0, v0, v1, vcc
	v_rsq_f32_e32 v40, v0
	s_nop 0
	v_mul_f32_e32 v20, 0x45800000, v40
	v_cndmask_b32_e32 v40, v40, v20, vcc
	v_pk_add_f32 v[22:23], v[218:219], 1.0 op_sel_hi:[1,0]
	v_pk_add_f32 v[20:21], v[216:217], 1.0 op_sel_hi:[1,0]
	v_pk_mul_f32 v[24:25], v[136:137], v[40:41] op_sel_hi:[1,0]
	v_pk_mul_f32 v[26:27], v[138:139], v[40:41] op_sel_hi:[1,0]
	v_pk_mul_f32 v[24:25], v[96:97], v[24:25]
	v_pk_mul_f32 v[26:27], v[98:99], v[26:27]
	v_pk_fma_f32 v[20:21], v[20:21], v[24:25], v[158:159]
	v_pk_fma_f32 v[22:23], v[22:23], v[26:27], v[160:161]
	v_cvt_pk_bf16_f32 v70, v20, v21
	v_cvt_pk_bf16_f32 v71, v22, v23
	global_store_dwordx2 v50, v[70:71], s[54:55]
	v_pk_mul_f32 v[24:25], v[140:141], v[40:41] op_sel_hi:[1,0]
	v_pk_mul_f32 v[26:27], v[142:143], v[40:41] op_sel_hi:[1,0]
	v_pk_mul_f32 v[24:25], v[24:25], v[100:101]
	v_pk_mul_f32 v[26:27], v[26:27], v[102:103]
	v_pk_add_f32 v[20:21], v[220:221], 1.0 op_sel_hi:[1,0]
	v_pk_add_f32 v[22:23], v[222:223], 1.0 op_sel_hi:[1,0]
	v_pk_fma_f32 v[20:21], v[24:25], v[20:21], v[162:163]
	v_pk_fma_f32 v[22:23], v[26:27], v[22:23], v[164:165]
	v_cvt_pk_bf16_f32 v72, v20, v21
	v_cvt_pk_bf16_f32 v73, v22, v23
	global_store_dwordx2 v50, v[72:73], s[54:55] offset:512
	v_pk_mul_f32 v[24:25], v[144:145], v[40:41] op_sel_hi:[1,0]
	v_pk_mul_f32 v[26:27], v[146:147], v[40:41] op_sel_hi:[1,0]
	v_pk_mul_f32 v[24:25], v[24:25], v[104:105]
	v_pk_mul_f32 v[26:27], v[26:27], v[106:107]
	v_pk_add_f32 v[20:21], v[224:225], 1.0 op_sel_hi:[1,0]
	v_pk_add_f32 v[22:23], v[226:227], 1.0 op_sel_hi:[1,0]
	v_pk_fma_f32 v[20:21], v[24:25], v[20:21], v[166:167]
	v_pk_fma_f32 v[22:23], v[26:27], v[22:23], v[168:169]
	v_cvt_pk_bf16_f32 v74, v20, v21
	v_cvt_pk_bf16_f32 v75, v22, v23
	global_store_dwordx2 v50, v[74:75], s[54:55] offset:1024
	v_pk_mul_f32 v[24:25], v[148:149], v[40:41] op_sel_hi:[1,0]
	v_pk_mul_f32 v[26:27], v[150:151], v[40:41] op_sel_hi:[1,0]
	v_pk_mul_f32 v[24:25], v[24:25], v[108:109]
	v_pk_mul_f32 v[26:27], v[26:27], v[110:111]
	v_pk_add_f32 v[20:21], v[228:229], 1.0 op_sel_hi:[1,0]
	v_pk_add_f32 v[22:23], v[230:231], 1.0 op_sel_hi:[1,0]
	v_pk_fma_f32 v[20:21], v[24:25], v[20:21], v[170:171]
	v_pk_fma_f32 v[22:23], v[26:27], v[22:23], v[172:173]
	v_cvt_pk_bf16_f32 v76, v20, v21
	v_cvt_pk_bf16_f32 v77, v22, v23
	global_store_dwordx2 v50, v[76:77], s[54:55] offset:1536
	s_cmp_lg_u32 s44, 0
	s_cbranch_scc0 .Lp0_done
	s_mov_b32 s45, 0
	s_cmp_ge_u32 s18, s47
	s_cbranch_scc1 .Lp0_skipB_3
	s_mov_b32 s45, 1
	s_add_i32 s19, s15, s60
	s_mul_hi_u32 s32, s19, 0x38e38e39
	s_lshr_b32 s32, s32, 9
	s_mul_i32 s11, s32, 0x900
	s_sub_i32 s61, s19, s11
	s_lshl_b32 s54, s19, 11
	s_add_u32 s54, s86, s54
	s_addc_u32 s55, s87, 0
	v_readlane_b32 s19, v255, 29
	s_nop 0
	s_add_i32 s32, s32, s19
	s_add_i32 s19, s61, 0xffffff00
	s_cmp_lt_u32 s61, 0x100
	s_cselect_b32 s56, s58, s48
	s_cselect_b32 s57, s59, s49
	s_cselect_b32 s11, 20, 23
	s_cselect_b32 s79, 32, s32
	s_cselect_b32 s19, s61, s19
	s_lshl_b32 s32, s32, s11
	s_lshl_b32 s19, s19, 12
	s_add_u32 s32, s32, s19
	s_add_u32 s56, s56, s32
	s_addc_u32 s57, s57, 0
	s_add_i32 s79, s79, s10
	s_mul_i32 s79, s79, 0x3000
	v_readlane_b32 s19, v253, 21
	v_readlane_b32 s32, v253, 22
	s_nop 0
	s_add_u32 s50, s19, s79
	s_addc_u32 s51, s32, 0
	s_add_u32 s52, s50, 0x1000
	s_addc_u32 s53, s51, 0
	global_load_dwordx4 v[136:139], v156, s[56:57]
	global_load_dwordx4 v[140:143], v156, s[56:57] offset:1024
	global_load_dwordx4 v[144:147], v156, s[56:57] offset:2048
	global_load_dwordx4 v[148:151], v156, s[56:57] offset:3072
	s_cmp_eq_u32 s50, s99
	s_cbranch_scc1 .Lp0_skipB_3_same
	s_mov_b32 s99, s50
	global_load_dwordx4 v[216:219], v156, s[52:53]
	global_load_dwordx4 v[158:161], v156, s[50:51]
	global_load_dwordx4 v[220:223], v156, s[52:53] offset:1024
	global_load_dwordx4 v[162:165], v156, s[50:51] offset:1024
	global_load_dwordx4 v[224:227], v156, s[52:53] offset:2048
	global_load_dwordx4 v[166:169], v156, s[50:51] offset:2048
	global_load_dwordx4 v[228:231], v156, s[52:53] offset:3072
	global_load_dwordx4 v[170:173], v156, s[50:51] offset:3072

; DEV void norm_item(const Params& p, int l, int g, int item, int tid) {
;     ...
;   float ss = 0.f;
; #pragma unroll
;   for (int i = 0; i < 4; ++i) {
;     v[i] = *(const float4*)(src + i * 256 + lane * 4);
;     ss += v[i].x * v[i].x + v[i].y * v[i].y + v[i].z * v[i].z + v[i].w * v[i].w;
;   }
;   ss = wsum(ss, lane);
.Lp0_skipB_3:
	s_cmp_lg_u32 s45, 0
	s_cbranch_scc0 .Lp0_w2
	s_waitcnt vmcnt(8)
	s_branch .Lp0_x2

; __global__ void __launch_bounds__(512) mega(Params p, int coop) {
;   __shared__ __attribute__((aligned(16))) char smem[147456 + 16];
	.amdhsa_kernel _Z4mega6Paramsi
		.amdhsa_group_segment_fixed_size 147472
		.amdhsa_private_segment_fixed_size 0
		.amdhsa_kernarg_size 584
		.amdhsa_user_sgpr_count 2
		.amdhsa_user_sgpr_dispatch_ptr 0
		.amdhsa_user_sgpr_queue_ptr 0
		.amdhsa_user_sgpr_kernarg_segment_ptr 1
		.amdhsa_user_sgpr_dispatch_id 0
		.amdhsa_user_sgpr_kernarg_preload_length 0
		.amdhsa_user_sgpr_kernarg_preload_offset 0
		.amdhsa_user_sgpr_private_segment_size 0
		.amdhsa_uses_dynamic_stack 0
		.amdhsa_enable_private_segment 0
		.amdhsa_system_sgpr_workgroup_id_x 1
		.amdhsa_system_sgpr_workgroup_id_y 0
		.amdhsa_system_sgpr_workgroup_id_z 0
		.amdhsa_system_sgpr_workgroup_info 0
		.amdhsa_system_vgpr_workitem_id 2
		.amdhsa_next_free_vgpr 256
		.amdhsa_next_free_sgpr 102
		.amdhsa_accum_offset 256
		.amdhsa_reserve_vcc 1
		.amdhsa_float_round_mode_32 0
		.amdhsa_float_round_mode_16_64 0
		.amdhsa_float_denorm_mode_32 3
		.amdhsa_float_denorm_mode_16_64 3
		.amdhsa_dx10_clamp 1
		.amdhsa_ieee_mode 1
		.amdhsa_fp16_overflow 0
		.amdhsa_tg_split 0
		.amdhsa_exception_fp_ieee_invalid_op 0
		.amdhsa_exception_fp_denorm_src 0
		.amdhsa_exception_fp_ieee_div_zero 0
		.amdhsa_exception_fp_ieee_overflow 0
		.amdhsa_exception_fp_ieee_underflow 0
		.amdhsa_exception_fp_ieee_inexact 0
		.amdhsa_exception_int_div_zero 0
	.end_amdhsa_kernel

; __global__ void __launch_bounds__(512) mega(Params p, int coop) {
amdhsa.kernels:
  - .agpr_count:     0
    .args:
      - .offset:         0
        .size:           320
        .value_kind:     by_value
      - .offset:         320
        .size:           4
        .value_kind:     by_value
      - .offset:         328
        .size:           4
        .value_kind:     hidden_block_count_x
      - .offset:         332
        .size:           4
        .value_kind:     hidden_block_count_y
      - .offset:         336
        .size:           4
        .value_kind:     hidden_block_count_z
      - .offset:         340
        .size:           2
        .value_kind:     hidden_group_size_x
      - .offset:         342
        .size:           2
        .value_kind:     hidden_group_size_y
      - .offset:         344
        .size:           2
        .value_kind:     hidden_group_size_z
      - .offset:         346
        .size:           2
        .value_kind:     hidden_remainder_x
      - .offset:         348
        .size:           2
        .value_kind:     hidden_remainder_y
      - .offset:         350
        .size:           2
        .value_kind:     hidden_remainder_z
      - .offset:         368
        .size:           8
        .value_kind:     hidden_global_offset_x
      - .offset:         376
        .size:           8
        .value_kind:     hidden_global_offset_y
      - .offset:         384
        .size:           8
        .value_kind:     hidden_global_offset_z
      - .offset:         392
        .size:           2
        .value_kind:     hidden_grid_dims
      - .offset:         416
        .size:           8
        .value_kind:     hidden_multigrid_sync_arg
    .group_segment_fixed_size: 147472
    .kernarg_segment_align: 8
    .kernarg_segment_size: 584
    .language:       OpenCL C
    .language_version:
      - 2
      - 0
    .max_flat_workgroup_size: 512
    .name:           _Z4mega6Paramsi
    .private_segment_fixed_size: 0
    .sgpr_count:     108
    .sgpr_spill_count: 188
    .symbol:         _Z4mega6Paramsi.kd
    .uniform_work_group_size: 1
    .uses_dynamic_stack: false
    .vgpr_count:     256
    .vgpr_spill_count: 0
    .wavefront_size: 64
